# v63 plus prompt memory-attention tile (phase 2): the 16 gate loads of its epilogue issued together with a counted vmcnt(15) instead of load, vmcnt(0), use per piece
# speedup vs baseline: 1.0051x; 1.0051x over previous
.LBB0_728:
	v_add_co_u32_e32 v64, vcc, s51, v194
	global_load_dwordx4 v[156:159], v[194:195], off
	global_load_dwordx4 v[152:155], v[194:195], off offset:1024
	global_load_dwordx4 v[148:151], v[194:195], off offset:2048
	global_load_dwordx4 v[144:147], v[194:195], off offset:3072
	v_addc_co_u32_e32 v65, vcc, 0, v195, vcc
	global_load_dwordx4 v[160:163], v[64:65], off
	global_load_dwordx4 v[164:167], v[64:65], off offset:1024
	global_load_dwordx4 v[168:171], v[64:65], off offset:2048
	global_load_dwordx4 v[172:175], v[64:65], off offset:3072
	s_waitcnt vmcnt(15)
	v_mfma_f32_32x32x16_bf16 v[64:79], v[120:123], v[104:107], 0
	s_add_i32 s5, s7, 2
	s_cmp_lt_u32 s7, 6
	s_cselect_b64 s[8:9], -1, 0
	s_and_b64 vcc, s[8:9], exec
	s_cselect_b32 s94, s4, 0x7000
	s_lshl_b64 s[8:9], s[94:95], 1
	s_add_u32 s8, s2, s8
	s_waitcnt vmcnt(14)
	v_mfma_f32_32x32x16_bf16 v[64:79], v[116:119], v[80:83], v[64:79]
	s_addc_u32 s9, s3, s9
	s_waitcnt vmcnt(13)
	v_mfma_f32_32x32x16_bf16 v[64:79], v[112:115], v[84:87], v[64:79]
	s_waitcnt vmcnt(12)
	v_mfma_f32_32x32x16_bf16 v[64:79], v[124:127], v[88:91], v[64:79]
	s_waitcnt vmcnt(11)
	v_mfma_f32_32x32x16_bf16 v[64:79], v[128:131], v[92:95], v[64:79]
	s_waitcnt vmcnt(10)
	v_mfma_f32_32x32x16_bf16 v[64:79], v[132:135], v[96:99], v[64:79]
	s_waitcnt vmcnt(9)
	v_mfma_f32_32x32x16_bf16 v[64:79], v[136:139], v[100:103], v[64:79]
	s_waitcnt vmcnt(8)
	v_mfma_f32_32x32x16_bf16 v[64:79], v[140:143], v[108:111], v[64:79]
	s_nop 11
	v_max_f32_e32 v112, v65, v65
	v_max_f32_e32 v113, v64, v64
	v_max_f32_e32 v112, v113, v112
	v_max3_f32 v112, v112, v66, v67
	v_max3_f32 v112, v112, v68, v69
	v_max3_f32 v112, v112, v70, v71
	v_max3_f32 v112, v112, v72, v73
	v_max3_f32 v112, v112, v74, v75
	v_max3_f32 v112, v112, v76, v77
	v_max3_f32 v112, v112, v78, v79
	ds_bpermute_b32 v113, v181, v112
	s_waitcnt lgkmcnt(0)
	v_max3_f32 v234, v232, v112, v113
	v_mul_f32_e32 v113, 0xbfb8aa3b, v234
	v_fmamk_f32 v64, v64, 0x3fb8aa3b, v113
	v_exp_f32_e32 v114, v64
	v_fmamk_f32 v65, v65, 0x3fb8aa3b, v113
	v_exp_f32_e32 v65, v65
	v_fmamk_f32 v66, v66, 0x3fb8aa3b, v113
	v_exp_f32_e32 v66, v66
	v_fmamk_f32 v67, v67, 0x3fb8aa3b, v113
	v_exp_f32_e32 v67, v67
	v_fmamk_f32 v68, v68, 0x3fb8aa3b, v113
	v_add_f32_e32 v64, 0, v114
	v_exp_f32_e32 v115, v68
	v_fmamk_f32 v68, v69, 0x3fb8aa3b, v113
	v_add_f32_e32 v64, v65, v64
	v_exp_f32_e32 v116, v68
	v_fmamk_f32 v68, v70, 0x3fb8aa3b, v113
	v_add_f32_e32 v64, v66, v64
	v_exp_f32_e32 v117, v68
	v_fmamk_f32 v68, v71, 0x3fb8aa3b, v113
	v_add_f32_e32 v64, v67, v64
	v_exp_f32_e32 v71, v68
	v_fmamk_f32 v68, v72, 0x3fb8aa3b, v113
	v_add_f32_e32 v64, v115, v64
	v_exp_f32_e32 v72, v68
	v_fmamk_f32 v68, v73, 0x3fb8aa3b, v113
	v_add_f32_e32 v64, v116, v64
	v_exp_f32_e32 v73, v68
	v_fmamk_f32 v68, v74, 0x3fb8aa3b, v113
	v_add_f32_e32 v64, v117, v64
	v_exp_f32_e32 v74, v68
	v_fmamk_f32 v68, v75, 0x3fb8aa3b, v113
	v_add_f32_e32 v64, v71, v64
	v_exp_f32_e32 v75, v68
	v_fmamk_f32 v68, v76, 0x3fb8aa3b, v113
	v_add_f32_e32 v64, v72, v64
	v_exp_f32_e32 v76, v68
	v_fmamk_f32 v68, v77, 0x3fb8aa3b, v113
	v_add_f32_e32 v64, v73, v64
	v_exp_f32_e32 v77, v68
	v_fmamk_f32 v68, v78, 0x3fb8aa3b, v113
	v_add_f32_e32 v64, v74, v64
	v_exp_f32_e32 v78, v68
	v_fmac_f32_e32 v113, 0x3fb8aa3b, v79
	v_add_f32_e32 v64, v75, v64
	v_exp_f32_e32 v79, v113
	v_add_f32_e32 v64, v76, v64
	v_sub_f32_e32 v112, v232, v234
	v_add_f32_e32 v64, v77, v64
	v_mul_f32_e32 v112, 0x3fb8aa3b, v112
	v_add_f32_e32 v64, v78, v64
	v_add_f32_e32 v233, v79, v64
	v_exp_f32_e32 v64, v112
	v_cvt_pk_bf16_f32 v68, v114, v65
	v_cvt_pk_bf16_f32 v69, v66, v67
	v_cvt_pk_bf16_f32 v70, v115, v116
	v_fmac_f32_e32 v233, v231, v64
	v_pk_mul_f32 v[62:63], v[62:63], v[64:65] op_sel_hi:[1,0]
	v_pk_mul_f32 v[60:61], v[60:61], v[64:65] op_sel_hi:[1,0]
	v_pk_mul_f32 v[58:59], v[58:59], v[64:65] op_sel_hi:[1,0]
	v_pk_mul_f32 v[56:57], v[56:57], v[64:65] op_sel_hi:[1,0]
	v_pk_mul_f32 v[54:55], v[54:55], v[64:65] op_sel_hi:[1,0]
	v_pk_mul_f32 v[52:53], v[52:53], v[64:65] op_sel_hi:[1,0]
	v_pk_mul_f32 v[50:51], v[50:51], v[64:65] op_sel_hi:[1,0]
	v_pk_mul_f32 v[48:49], v[48:49], v[64:65] op_sel_hi:[1,0]
	v_pk_mul_f32 v[46:47], v[46:47], v[64:65] op_sel_hi:[1,0]
	v_pk_mul_f32 v[44:45], v[44:45], v[64:65] op_sel_hi:[1,0]
	v_pk_mul_f32 v[42:43], v[42:43], v[64:65] op_sel_hi:[1,0]
	v_pk_mul_f32 v[40:41], v[40:41], v[64:65] op_sel_hi:[1,0]
	v_pk_mul_f32 v[38:39], v[38:39], v[64:65] op_sel_hi:[1,0]
	v_pk_mul_f32 v[36:37], v[36:37], v[64:65] op_sel_hi:[1,0]
	v_pk_mul_f32 v[34:35], v[34:35], v[64:65] op_sel_hi:[1,0]
	v_pk_mul_f32 v[32:33], v[32:33], v[64:65] op_sel_hi:[1,0]
	v_pk_mul_f32 v[30:31], v[30:31], v[64:65] op_sel_hi:[1,0]
	v_pk_mul_f32 v[28:29], v[28:29], v[64:65] op_sel_hi:[1,0]
	v_pk_mul_f32 v[26:27], v[26:27], v[64:65] op_sel_hi:[1,0]
	v_pk_mul_f32 v[24:25], v[24:25], v[64:65] op_sel_hi:[1,0]
	v_pk_mul_f32 v[22:23], v[22:23], v[64:65] op_sel_hi:[1,0]
	v_pk_mul_f32 v[20:21], v[20:21], v[64:65] op_sel_hi:[1,0]
	v_pk_mul_f32 v[18:19], v[18:19], v[64:65] op_sel_hi:[1,0]
	v_pk_mul_f32 v[16:17], v[16:17], v[64:65] op_sel_hi:[1,0]
	v_pk_mul_f32 v[14:15], v[14:15], v[64:65] op_sel_hi:[1,0]
	v_pk_mul_f32 v[12:13], v[12:13], v[64:65] op_sel_hi:[1,0]
	v_pk_mul_f32 v[10:11], v[10:11], v[64:65] op_sel_hi:[1,0]
	v_pk_mul_f32 v[8:9], v[8:9], v[64:65] op_sel_hi:[1,0]
	v_pk_mul_f32 v[6:7], v[6:7], v[64:65] op_sel_hi:[1,0]
	v_pk_mul_f32 v[4:5], v[4:5], v[64:65] op_sel_hi:[1,0]
	v_pk_mul_f32 v[2:3], v[2:3], v[64:65] op_sel_hi:[1,0]
	v_pk_mul_f32 v[0:1], v[0:1], v[64:65] op_sel_hi:[1,0]
	v_cvt_pk_bf16_f32 v64, v72, v73
	v_cvt_pk_bf16_f32 v65, v74, v75
	ds_read_b64_tr_b16 v[72:73], v230
	ds_read_b64_tr_b16 v[74:75], v230 offset:2560
	v_cvt_pk_bf16_f32 v71, v117, v71
	v_cvt_pk_bf16_f32 v66, v76, v77
	v_cvt_pk_bf16_f32 v67, v78, v79
	s_waitcnt lgkmcnt(0)
	v_mfma_f32_32x32x16_bf16 v[48:63], v[72:75], v[68:71], v[48:63]
	ds_read_b64_tr_b16 v[72:73], v230 offset:5120
	ds_read_b64_tr_b16 v[74:75], v230 offset:7680
	s_waitcnt lgkmcnt(0)
	v_mfma_f32_32x32x16_bf16 v[48:63], v[72:75], v[64:67], v[48:63]
	ds_read_b64_tr_b16 v[72:73], v230 offset:64
	ds_read_b64_tr_b16 v[74:75], v230 offset:2624
	s_waitcnt lgkmcnt(0)
	v_mfma_f32_32x32x16_bf16 v[32:47], v[72:75], v[68:71], v[32:47]
	ds_read_b64_tr_b16 v[72:73], v230 offset:5184
	ds_read_b64_tr_b16 v[74:75], v230 offset:7744
	s_waitcnt lgkmcnt(0)
	v_mfma_f32_32x32x16_bf16 v[32:47], v[72:75], v[64:67], v[32:47]
	ds_read_b64_tr_b16 v[72:73], v230 offset:128
	ds_read_b64_tr_b16 v[74:75], v230 offset:2688
	s_waitcnt lgkmcnt(0)
	v_mfma_f32_32x32x16_bf16 v[16:31], v[72:75], v[68:71], v[16:31]
	ds_read_b64_tr_b16 v[72:73], v230 offset:5248
	ds_read_b64_tr_b16 v[74:75], v230 offset:7808
	s_waitcnt lgkmcnt(0)
	v_mfma_f32_32x32x16_bf16 v[16:31], v[72:75], v[64:67], v[16:31]
	ds_read_b64_tr_b16 v[72:73], v230 offset:192
	ds_read_b64_tr_b16 v[74:75], v230 offset:2752
	s_waitcnt lgkmcnt(0)
	v_mfma_f32_32x32x16_bf16 v[0:15], v[72:75], v[68:71], v[0:15]
	ds_read_b64_tr_b16 v[68:69], v230 offset:5312
	ds_read_b64_tr_b16 v[70:71], v230 offset:7872
	s_waitcnt lgkmcnt(0)
	v_mfma_f32_32x32x16_bf16 v[0:15], v[68:71], v[64:67], v[0:15]
	v_lshl_add_u64 v[64:65], s[8:9], 0, v[176:177]
	global_load_dwordx4 v[120:123], v[64:65], off
	global_load_dwordx4 v[116:119], v[64:65], off offset:1024
	global_load_dwordx4 v[112:115], v[64:65], off offset:2048
	global_load_dwordx4 v[124:127], v[64:65], off offset:3072
	v_lshl_add_u64 v[64:65], s[8:9], 0, v[186:187]
	global_load_dwordx4 v[128:131], v[64:65], off
	v_lshl_add_u64 v[64:65], s[8:9], 0, v[188:189]
	global_load_dwordx4 v[132:135], v[64:65], off
	v_lshl_add_u64 v[64:65], s[8:9], 0, v[190:191]
	global_load_dwordx4 v[136:139], v[64:65], off
	v_lshl_add_u64 v[64:65], s[8:9], 0, v[192:193]
	global_load_dwordx4 v[140:143], v[64:65], off
	s_waitcnt vmcnt(15)
	v_mfma_f32_32x32x16_bf16 v[64:79], v[156:159], v[104:107], 0
	s_mov_b64 s[8:9], 0x4000
	s_addk_i32 s4, 0x2000
	v_lshl_add_u64 v[194:195], v[194:195], 0, s[8:9]
	s_mov_b32 s7, s5
	s_waitcnt vmcnt(14)
	v_mfma_f32_32x32x16_bf16 v[64:79], v[152:155], v[80:83], v[64:79]
	s_waitcnt vmcnt(13)
	v_mfma_f32_32x32x16_bf16 v[64:79], v[148:151], v[84:87], v[64:79]
	s_waitcnt vmcnt(12)
	v_mfma_f32_32x32x16_bf16 v[64:79], v[144:147], v[88:91], v[64:79]
	s_waitcnt vmcnt(11)
	v_mfma_f32_32x32x16_bf16 v[64:79], v[160:163], v[92:95], v[64:79]
	s_waitcnt vmcnt(10)
	v_mfma_f32_32x32x16_bf16 v[64:79], v[164:167], v[96:99], v[64:79]
	s_waitcnt vmcnt(9)
	v_mfma_f32_32x32x16_bf16 v[64:79], v[168:171], v[100:103], v[64:79]
	s_waitcnt vmcnt(8)
	v_mfma_f32_32x32x16_bf16 v[64:79], v[172:175], v[108:111], v[64:79]
	s_nop 11
	v_max_f32_e32 v144, v65, v65
	v_max_f32_e32 v145, v64, v64
	v_max_f32_e32 v144, v145, v144
	v_max3_f32 v144, v144, v66, v67
	v_max3_f32 v144, v144, v68, v69
	v_max3_f32 v144, v144, v70, v71
	v_max3_f32 v144, v144, v72, v73
	v_max3_f32 v144, v144, v74, v75
	v_max3_f32 v144, v144, v76, v77
	v_max3_f32 v144, v144, v78, v79
	ds_bpermute_b32 v145, v181, v144
	s_waitcnt lgkmcnt(0)
	v_max3_f32 v232, v234, v144, v145
	v_mul_f32_e32 v145, 0xbfb8aa3b, v232
	v_fmamk_f32 v64, v64, 0x3fb8aa3b, v145
	v_exp_f32_e32 v146, v64
	v_fmamk_f32 v65, v65, 0x3fb8aa3b, v145
	v_exp_f32_e32 v65, v65
	v_fmamk_f32 v66, v66, 0x3fb8aa3b, v145
	v_exp_f32_e32 v66, v66
	v_fmamk_f32 v67, v67, 0x3fb8aa3b, v145
	v_exp_f32_e32 v67, v67
	v_fmamk_f32 v68, v68, 0x3fb8aa3b, v145
	v_add_f32_e32 v64, 0, v146
	v_exp_f32_e32 v147, v68
	v_fmamk_f32 v68, v69, 0x3fb8aa3b, v145
	v_add_f32_e32 v64, v65, v64
	v_exp_f32_e32 v148, v68
	v_fmamk_f32 v68, v70, 0x3fb8aa3b, v145
	v_add_f32_e32 v64, v66, v64
	v_exp_f32_e32 v149, v68
	v_fmamk_f32 v68, v71, 0x3fb8aa3b, v145
	v_add_f32_e32 v64, v67, v64
	v_exp_f32_e32 v71, v68
	v_fmamk_f32 v68, v72, 0x3fb8aa3b, v145
	v_add_f32_e32 v64, v147, v64
	v_exp_f32_e32 v72, v68
	v_fmamk_f32 v68, v73, 0x3fb8aa3b, v145
	v_add_f32_e32 v64, v148, v64
	v_exp_f32_e32 v73, v68
	v_fmamk_f32 v68, v74, 0x3fb8aa3b, v145
	v_add_f32_e32 v64, v149, v64
	v_exp_f32_e32 v74, v68
	v_fmamk_f32 v68, v75, 0x3fb8aa3b, v145
	v_add_f32_e32 v64, v71, v64
	v_exp_f32_e32 v75, v68
	v_fmamk_f32 v68, v76, 0x3fb8aa3b, v145
	v_add_f32_e32 v64, v72, v64
	v_exp_f32_e32 v76, v68
	v_fmamk_f32 v68, v77, 0x3fb8aa3b, v145
	v_add_f32_e32 v64, v73, v64
	v_exp_f32_e32 v77, v68
	v_fmamk_f32 v68, v78, 0x3fb8aa3b, v145
	v_add_f32_e32 v64, v74, v64
	v_exp_f32_e32 v78, v68
	v_fmac_f32_e32 v145, 0x3fb8aa3b, v79
	v_add_f32_e32 v64, v75, v64
	v_exp_f32_e32 v79, v145
	v_add_f32_e32 v64, v76, v64
	v_sub_f32_e32 v144, v234, v232
	v_add_f32_e32 v64, v77, v64
	v_mul_f32_e32 v144, 0x3fb8aa3b, v144
	v_add_f32_e32 v64, v78, v64
	v_add_f32_e32 v231, v79, v64
	v_exp_f32_e32 v64, v144
	v_cvt_pk_bf16_f32 v68, v146, v65
	v_cvt_pk_bf16_f32 v69, v66, v67
	v_cvt_pk_bf16_f32 v70, v147, v148
	v_fmac_f32_e32 v231, v233, v64
	v_pk_mul_f32 v[62:63], v[62:63], v[64:65] op_sel_hi:[1,0]
	v_pk_mul_f32 v[60:61], v[60:61], v[64:65] op_sel_hi:[1,0]
	v_pk_mul_f32 v[58:59], v[58:59], v[64:65] op_sel_hi:[1,0]
	v_pk_mul_f32 v[56:57], v[56:57], v[64:65] op_sel_hi:[1,0]
	v_pk_mul_f32 v[54:55], v[54:55], v[64:65] op_sel_hi:[1,0]
	v_pk_mul_f32 v[52:53], v[52:53], v[64:65] op_sel_hi:[1,0]
	v_pk_mul_f32 v[50:51], v[50:51], v[64:65] op_sel_hi:[1,0]
	v_pk_mul_f32 v[48:49], v[48:49], v[64:65] op_sel_hi:[1,0]
	v_pk_mul_f32 v[46:47], v[46:47], v[64:65] op_sel_hi:[1,0]
	v_pk_mul_f32 v[44:45], v[44:45], v[64:65] op_sel_hi:[1,0]
	v_pk_mul_f32 v[42:43], v[42:43], v[64:65] op_sel_hi:[1,0]
	v_pk_mul_f32 v[40:41], v[40:41], v[64:65] op_sel_hi:[1,0]
	v_pk_mul_f32 v[38:39], v[38:39], v[64:65] op_sel_hi:[1,0]
	v_pk_mul_f32 v[36:37], v[36:37], v[64:65] op_sel_hi:[1,0]
	v_pk_mul_f32 v[34:35], v[34:35], v[64:65] op_sel_hi:[1,0]
	v_pk_mul_f32 v[32:33], v[32:33], v[64:65] op_sel_hi:[1,0]
	v_pk_mul_f32 v[30:31], v[30:31], v[64:65] op_sel_hi:[1,0]
	v_pk_mul_f32 v[28:29], v[28:29], v[64:65] op_sel_hi:[1,0]
	v_pk_mul_f32 v[26:27], v[26:27], v[64:65] op_sel_hi:[1,0]
	v_pk_mul_f32 v[24:25], v[24:25], v[64:65] op_sel_hi:[1,0]
	v_pk_mul_f32 v[22:23], v[22:23], v[64:65] op_sel_hi:[1,0]
	v_pk_mul_f32 v[20:21], v[20:21], v[64:65] op_sel_hi:[1,0]
	v_pk_mul_f32 v[18:19], v[18:19], v[64:65] op_sel_hi:[1,0]
	v_pk_mul_f32 v[16:17], v[16:17], v[64:65] op_sel_hi:[1,0]
	v_pk_mul_f32 v[14:15], v[14:15], v[64:65] op_sel_hi:[1,0]
	v_pk_mul_f32 v[12:13], v[12:13], v[64:65] op_sel_hi:[1,0]
	v_pk_mul_f32 v[10:11], v[10:11], v[64:65] op_sel_hi:[1,0]
	v_pk_mul_f32 v[8:9], v[8:9], v[64:65] op_sel_hi:[1,0]
	v_pk_mul_f32 v[6:7], v[6:7], v[64:65] op_sel_hi:[1,0]
	v_pk_mul_f32 v[4:5], v[4:5], v[64:65] op_sel_hi:[1,0]
	v_pk_mul_f32 v[2:3], v[2:3], v[64:65] op_sel_hi:[1,0]
	v_pk_mul_f32 v[0:1], v[0:1], v[64:65] op_sel_hi:[1,0]
	v_cvt_pk_bf16_f32 v64, v72, v73
	v_cvt_pk_bf16_f32 v65, v74, v75
	ds_read_b64_tr_b16 v[72:73], v230 offset:10240
	ds_read_b64_tr_b16 v[74:75], v230 offset:12800
	v_cvt_pk_bf16_f32 v71, v149, v71
	v_cvt_pk_bf16_f32 v66, v76, v77
	v_cvt_pk_bf16_f32 v67, v78, v79
	s_waitcnt lgkmcnt(0)
	v_mfma_f32_32x32x16_bf16 v[48:63], v[72:75], v[68:71], v[48:63]
	ds_read_b64_tr_b16 v[72:73], v230 offset:15360
	ds_read_b64_tr_b16 v[74:75], v230 offset:17920
	s_waitcnt lgkmcnt(0)
	v_mfma_f32_32x32x16_bf16 v[48:63], v[72:75], v[64:67], v[48:63]
	ds_read_b64_tr_b16 v[72:73], v230 offset:10304
	ds_read_b64_tr_b16 v[74:75], v230 offset:12864
	s_waitcnt lgkmcnt(0)
	v_mfma_f32_32x32x16_bf16 v[32:47], v[72:75], v[68:71], v[32:47]
	ds_read_b64_tr_b16 v[72:73], v230 offset:15424
	ds_read_b64_tr_b16 v[74:75], v230 offset:17984
	s_waitcnt lgkmcnt(0)
	v_mfma_f32_32x32x16_bf16 v[32:47], v[72:75], v[64:67], v[32:47]
	ds_read_b64_tr_b16 v[72:73], v230 offset:10368
	ds_read_b64_tr_b16 v[74:75], v230 offset:12928
	s_waitcnt lgkmcnt(0)
	v_mfma_f32_32x32x16_bf16 v[16:31], v[72:75], v[68:71], v[16:31]
	ds_read_b64_tr_b16 v[72:73], v230 offset:15488
	ds_read_b64_tr_b16 v[74:75], v230 offset:18048
	s_waitcnt lgkmcnt(0)
	v_mfma_f32_32x32x16_bf16 v[16:31], v[72:75], v[64:67], v[16:31]
	ds_read_b64_tr_b16 v[72:73], v230 offset:10432
	ds_read_b64_tr_b16 v[74:75], v230 offset:12992
	s_waitcnt lgkmcnt(0)
	v_mfma_f32_32x32x16_bf16 v[0:15], v[72:75], v[68:71], v[0:15]
	ds_read_b64_tr_b16 v[68:69], v230 offset:15552
	ds_read_b64_tr_b16 v[70:71], v230 offset:18112
	v_add_u32_e32 v230, 0x5000, v230
	s_waitcnt lgkmcnt(0)
	v_mfma_f32_32x32x16_bf16 v[0:15], v[68:71], v[64:67], v[0:15]
	s_cbranch_vccnz .LBB0_728
	ds_bpermute_b32 v64, v181, v231
	s_movk_i32 s4, 0x1c00
	s_lshl_b32 s94, s6, 1
	v_lshlrev_b32_e32 v176, 3, v178
	s_waitcnt lgkmcnt(0)
	v_add_f32_e32 v64, v231, v64
	v_div_scale_f32 v65, s[2:3], v64, v64, 1.0
	v_rcp_f32_e32 v66, v65
	s_nop 0
	v_fma_f32 v67, -v65, v66, 1.0
	v_fmac_f32_e32 v66, v67, v66
	v_div_scale_f32 v67, vcc, 1.0, v64, 1.0
	v_mul_f32_e32 v68, v67, v66
	v_fma_f32 v69, -v65, v68, v67
	v_fmac_f32_e32 v68, v69, v66
	v_fma_f32 v65, -v65, v68, v67
	v_div_fmas_f32 v65, v65, v66, v68
	v_mov_b64_e32 v[68:69], s[96:97]
	v_mad_u64_u32 v[68:69], s[2:3], v182, s4, v[68:69]
	v_mov_b32_e32 v70, v69
	v_lshl_add_u64 v[66:67], v[184:185], 0, s[94:95]
	v_mad_u64_u32 v[70:71], s[2:3], v183, s4, v[70:71]
	v_mov_b32_e32 v69, v70
	v_lshl_add_u64 v[70:71], v[66:67], 0, v[176:177]
	s_mov_b64 s[2:3], 0x5400
	v_lshl_add_u64 v[66:67], v[70:71], 0, s[2:3]
	s_movk_i32 s2, 0x5000
	v_add_co_u32_e32 v70, vcc, s2, v70
	v_div_fixup_f32 v64, v65, v64, 1.0
	s_nop 0
	v_addc_co_u32_e32 v71, vcc, 0, v71, vcc
	global_load_dwordx2 v[80:81], v[66:67], off
	global_load_dwordx2 v[82:83], v[66:67], off offset:16
	global_load_dwordx2 v[84:85], v[66:67], off offset:32
	global_load_dwordx2 v[86:87], v[66:67], off offset:48
	global_load_dwordx2 v[88:89], v[66:67], off offset:64
	global_load_dwordx2 v[90:91], v[66:67], off offset:80
	global_load_dwordx2 v[92:93], v[66:67], off offset:96
	global_load_dwordx2 v[94:95], v[66:67], off offset:112
	global_load_dwordx2 v[96:97], v[66:67], off offset:128
	global_load_dwordx2 v[98:99], v[66:67], off offset:144
	global_load_dwordx2 v[100:101], v[66:67], off offset:160
	global_load_dwordx2 v[102:103], v[66:67], off offset:176
	global_load_dwordx2 v[104:105], v[66:67], off offset:192
	global_load_dwordx2 v[106:107], v[66:67], off offset:208
	global_load_dwordx2 v[108:109], v[66:67], off offset:224
	global_load_dwordx2 v[110:111], v[66:67], off offset:240
	v_lshl_add_u64 v[68:69], v[68:69], 0, s[94:95]
	s_mov_b64 s[2:3], 0x1d301800
	s_waitcnt vmcnt(15)
	v_mov_b32_e32 v70, v80
	v_mov_b32_e32 v71, v81
	v_lshlrev_b32_e32 v72, 16, v70
	v_mul_f32_e32 v65, 0xbfb8aa3b, v72
	v_exp_f32_e32 v65, v65
	v_and_b32_e32 v73, 0xffff0000, v70
	v_add_f32_e32 v65, 1.0, v65
	v_rcp_f32_e32 v74, v65
	v_pk_mul_f32 v[48:49], v[48:49], v[64:65] op_sel_hi:[1,0]
	v_mul_f32_e32 v65, 0xbfb8aa3b, v73
	v_exp_f32_e32 v65, v65
	s_nop 0
	v_add_f32_e32 v65, 1.0, v65
	v_rcp_f32_e32 v75, v65
	s_nop 0
	v_pk_mul_f32 v[72:73], v[74:75], v[72:73]
	s_nop 0
	v_pk_mul_f32 v[48:49], v[48:49], v[72:73]
	s_nop 0
	v_cvt_pk_bf16_f32 v70, v48, v49
	v_lshlrev_b32_e32 v48, 16, v71
	v_mul_f32_e32 v65, 0xbfb8aa3b, v48
	v_exp_f32_e32 v65, v65
	v_and_b32_e32 v49, 0xffff0000, v71
	v_add_f32_e32 v65, 1.0, v65
	v_rcp_f32_e32 v72, v65
	v_pk_mul_f32 v[50:51], v[50:51], v[64:65] op_sel_hi:[1,0]
	v_mul_f32_e32 v65, 0xbfb8aa3b, v49
	v_exp_f32_e32 v65, v65
	s_nop 0
	v_add_f32_e32 v65, 1.0, v65
	v_rcp_f32_e32 v73, v65
	v_pk_mul_f32 v[52:53], v[52:53], v[64:65] op_sel_hi:[1,0]
	v_pk_mul_f32 v[54:55], v[54:55], v[64:65] op_sel_hi:[1,0]
	v_pk_mul_f32 v[56:57], v[56:57], v[64:65] op_sel_hi:[1,0]
	v_pk_mul_f32 v[48:49], v[72:73], v[48:49]
	v_pk_mul_f32 v[32:33], v[32:33], v[64:65] op_sel_hi:[1,0]
	v_pk_mul_f32 v[48:49], v[50:51], v[48:49]
	v_lshl_add_u64 v[50:51], v[68:69], 0, v[176:177]
	v_cvt_pk_bf16_f32 v71, v48, v49
	v_lshl_add_u64 v[48:49], v[50:51], 0, s[2:3]
	s_mov_b32 s2, 0x1d301000
	v_add_co_u32_e32 v50, vcc, s2, v50
	v_pk_mul_f32 v[34:35], v[34:35], v[64:65] op_sel_hi:[1,0]
	s_nop 0
	v_addc_co_u32_e32 v51, vcc, 0, v51, vcc
	global_store_dwordx2 v[50:51], v[70:71], off offset:2048
	v_pk_mul_f32 v[36:37], v[36:37], v[64:65] op_sel_hi:[1,0]
	v_pk_mul_f32 v[38:39], v[38:39], v[64:65] op_sel_hi:[1,0]
	v_pk_mul_f32 v[16:17], v[16:17], v[64:65] op_sel_hi:[1,0]
	v_pk_mul_f32 v[18:19], v[18:19], v[64:65] op_sel_hi:[1,0]
	v_pk_mul_f32 v[20:21], v[20:21], v[64:65] op_sel_hi:[1,0]
	v_pk_mul_f32 v[22:23], v[22:23], v[64:65] op_sel_hi:[1,0]
	v_pk_mul_f32 v[0:1], v[0:1], v[64:65] op_sel_hi:[1,0]
	v_pk_mul_f32 v[2:3], v[2:3], v[64:65] op_sel_hi:[1,0]
	v_pk_mul_f32 v[4:5], v[4:5], v[64:65] op_sel_hi:[1,0]
	v_pk_mul_f32 v[6:7], v[6:7], v[64:65] op_sel_hi:[1,0]
	s_waitcnt vmcnt(15)
	v_mov_b32_e32 v50, v82
	v_mov_b32_e32 v51, v83
	v_lshlrev_b32_e32 v68, 16, v50
	v_and_b32_e32 v69, 0xffff0000, v50
	v_mul_f32_e32 v50, 0xbfb8aa3b, v68
	v_exp_f32_e32 v50, v50
	s_nop 0
	v_add_f32_e32 v50, 1.0, v50
	v_rcp_f32_e32 v70, v50
	v_mul_f32_e32 v50, 0xbfb8aa3b, v69
	v_exp_f32_e32 v50, v50
	s_nop 0
	v_add_f32_e32 v50, 1.0, v50
	v_rcp_f32_e32 v71, v50
	s_nop 0
	v_pk_mul_f32 v[68:69], v[70:71], v[68:69]
	s_nop 0
	v_pk_mul_f32 v[52:53], v[52:53], v[68:69]
	s_nop 0
	v_cvt_pk_bf16_f32 v50, v52, v53
	v_lshlrev_b32_e32 v52, 16, v51
	v_and_b32_e32 v53, 0xffff0000, v51
	v_mul_f32_e32 v51, 0xbfb8aa3b, v52
	v_exp_f32_e32 v51, v51
	s_nop 0
	v_add_f32_e32 v51, 1.0, v51
	v_rcp_f32_e32 v68, v51
	v_mul_f32_e32 v51, 0xbfb8aa3b, v53
	v_exp_f32_e32 v51, v51
	s_nop 0
	v_add_f32_e32 v51, 1.0, v51
	v_rcp_f32_e32 v69, v51
	s_nop 0
	v_pk_mul_f32 v[52:53], v[68:69], v[52:53]
	s_nop 0
	v_pk_mul_f32 v[52:53], v[54:55], v[52:53]
	s_nop 0
	v_cvt_pk_bf16_f32 v51, v52, v53
	global_store_dwordx2 v[48:49], v[50:51], off offset:16
	s_waitcnt vmcnt(15)
	v_mov_b32_e32 v50, v84
	v_mov_b32_e32 v51, v85
	v_lshlrev_b32_e32 v52, 16, v50
	v_and_b32_e32 v53, 0xffff0000, v50
	v_mul_f32_e32 v50, 0xbfb8aa3b, v52
	v_exp_f32_e32 v50, v50
	s_nop 0
	v_add_f32_e32 v50, 1.0, v50
	v_rcp_f32_e32 v54, v50
	v_mul_f32_e32 v50, 0xbfb8aa3b, v53
	v_exp_f32_e32 v50, v50
	s_nop 0
	v_add_f32_e32 v50, 1.0, v50
	v_rcp_f32_e32 v55, v50
	s_nop 0
	v_pk_mul_f32 v[52:53], v[54:55], v[52:53]
	s_nop 0
	v_pk_mul_f32 v[52:53], v[56:57], v[52:53]
	v_pk_mul_f32 v[56:57], v[58:59], v[64:65] op_sel_hi:[1,0]
	v_cvt_pk_bf16_f32 v50, v52, v53
	v_lshlrev_b32_e32 v52, 16, v51
	v_and_b32_e32 v53, 0xffff0000, v51
	v_mul_f32_e32 v51, 0xbfb8aa3b, v52
	v_exp_f32_e32 v51, v51
	s_nop 0
	v_add_f32_e32 v51, 1.0, v51
	v_rcp_f32_e32 v54, v51
	v_mul_f32_e32 v51, 0xbfb8aa3b, v53
	v_exp_f32_e32 v51, v51
	s_nop 0
	v_add_f32_e32 v51, 1.0, v51
	v_rcp_f32_e32 v55, v51
	s_nop 0
	v_pk_mul_f32 v[52:53], v[54:55], v[52:53]
	s_nop 0
	v_pk_mul_f32 v[52:53], v[56:57], v[52:53]
	v_pk_mul_f32 v[56:57], v[60:61], v[64:65] op_sel_hi:[1,0]
	v_cvt_pk_bf16_f32 v51, v52, v53
	global_store_dwordx2 v[48:49], v[50:51], off offset:32
	s_waitcnt vmcnt(15)
	v_mov_b32_e32 v50, v86
	v_mov_b32_e32 v51, v87
	v_lshlrev_b32_e32 v52, 16, v50
	v_and_b32_e32 v53, 0xffff0000, v50
	v_mul_f32_e32 v50, 0xbfb8aa3b, v52
	v_exp_f32_e32 v50, v50
	s_nop 0
	v_add_f32_e32 v50, 1.0, v50
	v_rcp_f32_e32 v54, v50
	v_mul_f32_e32 v50, 0xbfb8aa3b, v53
	v_exp_f32_e32 v50, v50
	s_nop 0
	v_add_f32_e32 v50, 1.0, v50
	v_rcp_f32_e32 v55, v50
	s_nop 0
	v_pk_mul_f32 v[52:53], v[54:55], v[52:53]
	s_nop 0
	v_pk_mul_f32 v[52:53], v[56:57], v[52:53]
	v_pk_mul_f32 v[56:57], v[62:63], v[64:65] op_sel_hi:[1,0]
	v_cvt_pk_bf16_f32 v50, v52, v53
	v_lshlrev_b32_e32 v52, 16, v51
	v_and_b32_e32 v53, 0xffff0000, v51
	v_mul_f32_e32 v51, 0xbfb8aa3b, v52
	v_exp_f32_e32 v51, v51
	s_nop 0
	v_add_f32_e32 v51, 1.0, v51
	v_rcp_f32_e32 v54, v51
	v_mul_f32_e32 v51, 0xbfb8aa3b, v53
	v_exp_f32_e32 v51, v51
	s_nop 0
	v_add_f32_e32 v51, 1.0, v51
	v_rcp_f32_e32 v55, v51
	s_nop 0
	v_pk_mul_f32 v[52:53], v[54:55], v[52:53]
	s_nop 0
	v_pk_mul_f32 v[52:53], v[56:57], v[52:53]
	s_nop 0
	v_cvt_pk_bf16_f32 v51, v52, v53
	global_store_dwordx2 v[48:49], v[50:51], off offset:48
	s_waitcnt vmcnt(15)
	v_mov_b32_e32 v50, v88
	v_mov_b32_e32 v51, v89
	v_lshlrev_b32_e32 v52, 16, v50
	v_and_b32_e32 v53, 0xffff0000, v50
	v_mul_f32_e32 v50, 0xbfb8aa3b, v52
	v_exp_f32_e32 v50, v50
	s_nop 0
	v_add_f32_e32 v50, 1.0, v50
	v_rcp_f32_e32 v54, v50
	v_mul_f32_e32 v50, 0xbfb8aa3b, v53
	v_exp_f32_e32 v50, v50
	s_nop 0
	v_add_f32_e32 v50, 1.0, v50
	v_rcp_f32_e32 v55, v50
	v_lshlrev_b32_e32 v50, 16, v51
	v_and_b32_e32 v51, 0xffff0000, v51
	v_pk_mul_f32 v[52:53], v[54:55], v[52:53]
	s_nop 0
	v_pk_mul_f32 v[32:33], v[32:33], v[52:53]
	s_nop 0
	v_cvt_pk_bf16_f32 v32, v32, v33
	v_mul_f32_e32 v33, 0xbfb8aa3b, v50
	v_exp_f32_e32 v33, v33
	s_nop 0
	v_add_f32_e32 v33, 1.0, v33
	v_rcp_f32_e32 v52, v33
	v_mul_f32_e32 v33, 0xbfb8aa3b, v51
	v_exp_f32_e32 v33, v33
	s_nop 0
	v_add_f32_e32 v33, 1.0, v33
	v_rcp_f32_e32 v53, v33
	s_nop 0
	v_pk_mul_f32 v[50:51], v[52:53], v[50:51]
	s_nop 0
	v_pk_mul_f32 v[34:35], v[34:35], v[50:51]
	s_nop 0
	v_cvt_pk_bf16_f32 v33, v34, v35
	global_store_dwordx2 v[48:49], v[32:33], off offset:64
	s_waitcnt vmcnt(15)
	v_mov_b32_e32 v32, v90
	v_mov_b32_e32 v33, v91
	v_lshlrev_b32_e32 v34, 16, v32
	v_and_b32_e32 v35, 0xffff0000, v32
	v_mul_f32_e32 v32, 0xbfb8aa3b, v34
	v_exp_f32_e32 v32, v32
	s_nop 0
	v_add_f32_e32 v32, 1.0, v32
	v_rcp_f32_e32 v50, v32
	v_mul_f32_e32 v32, 0xbfb8aa3b, v35
	v_exp_f32_e32 v32, v32
	s_nop 0
	v_add_f32_e32 v32, 1.0, v32
	v_rcp_f32_e32 v51, v32
	s_nop 0
	v_pk_mul_f32 v[34:35], v[50:51], v[34:35]
	s_nop 0
	v_pk_mul_f32 v[34:35], v[36:37], v[34:35]
	s_nop 0
	v_cvt_pk_bf16_f32 v32, v34, v35
	v_lshlrev_b32_e32 v34, 16, v33
	v_and_b32_e32 v35, 0xffff0000, v33
	v_mul_f32_e32 v33, 0xbfb8aa3b, v34
	v_exp_f32_e32 v33, v33
	s_nop 0
	v_add_f32_e32 v33, 1.0, v33
	v_rcp_f32_e32 v36, v33
	v_mul_f32_e32 v33, 0xbfb8aa3b, v35
	v_exp_f32_e32 v33, v33
	s_nop 0
	v_add_f32_e32 v33, 1.0, v33
	v_rcp_f32_e32 v37, v33
	s_nop 0
	v_pk_mul_f32 v[34:35], v[36:37], v[34:35]
	s_nop 0
	v_pk_mul_f32 v[34:35], v[38:39], v[34:35]
	v_pk_mul_f32 v[38:39], v[40:41], v[64:65] op_sel_hi:[1,0]
	v_cvt_pk_bf16_f32 v33, v34, v35
	global_store_dwordx2 v[48:49], v[32:33], off offset:80
	s_waitcnt vmcnt(15)
	v_mov_b32_e32 v32, v92
	v_mov_b32_e32 v33, v93
	v_lshlrev_b32_e32 v34, 16, v32
	v_and_b32_e32 v35, 0xffff0000, v32
	v_mul_f32_e32 v32, 0xbfb8aa3b, v34
	v_exp_f32_e32 v32, v32
	s_nop 0
	v_add_f32_e32 v32, 1.0, v32
	v_rcp_f32_e32 v36, v32
	v_mul_f32_e32 v32, 0xbfb8aa3b, v35
	v_exp_f32_e32 v32, v32
	s_nop 0
	v_add_f32_e32 v32, 1.0, v32
	v_rcp_f32_e32 v37, v32
	s_nop 0
	v_pk_mul_f32 v[34:35], v[36:37], v[34:35]
	s_nop 0
	v_pk_mul_f32 v[34:35], v[38:39], v[34:35]
	v_pk_mul_f32 v[38:39], v[42:43], v[64:65] op_sel_hi:[1,0]
	v_cvt_pk_bf16_f32 v32, v34, v35
	v_lshlrev_b32_e32 v34, 16, v33
	v_and_b32_e32 v35, 0xffff0000, v33
	v_mul_f32_e32 v33, 0xbfb8aa3b, v34
	v_exp_f32_e32 v33, v33
	s_nop 0
	v_add_f32_e32 v33, 1.0, v33
	v_rcp_f32_e32 v36, v33
	v_mul_f32_e32 v33, 0xbfb8aa3b, v35
	v_exp_f32_e32 v33, v33
	s_nop 0
	v_add_f32_e32 v33, 1.0, v33
	v_rcp_f32_e32 v37, v33
	s_nop 0
	v_pk_mul_f32 v[34:35], v[36:37], v[34:35]
	s_nop 0
	v_pk_mul_f32 v[34:35], v[38:39], v[34:35]
	v_pk_mul_f32 v[38:39], v[44:45], v[64:65] op_sel_hi:[1,0]
	v_cvt_pk_bf16_f32 v33, v34, v35
	global_store_dwordx2 v[48:49], v[32:33], off offset:96
	s_waitcnt vmcnt(15)
	v_mov_b32_e32 v32, v94
	v_mov_b32_e32 v33, v95
	v_lshlrev_b32_e32 v34, 16, v32
	v_and_b32_e32 v35, 0xffff0000, v32
	v_mul_f32_e32 v32, 0xbfb8aa3b, v34
	v_exp_f32_e32 v32, v32
	s_nop 0
	v_add_f32_e32 v32, 1.0, v32
	v_rcp_f32_e32 v36, v32
	v_mul_f32_e32 v32, 0xbfb8aa3b, v35
	v_exp_f32_e32 v32, v32
	s_nop 0
	v_add_f32_e32 v32, 1.0, v32
	v_rcp_f32_e32 v37, v32
	s_nop 0
	v_pk_mul_f32 v[34:35], v[36:37], v[34:35]
	s_nop 0
	v_pk_mul_f32 v[34:35], v[38:39], v[34:35]
	v_pk_mul_f32 v[38:39], v[46:47], v[64:65] op_sel_hi:[1,0]
	v_cvt_pk_bf16_f32 v32, v34, v35
	v_lshlrev_b32_e32 v34, 16, v33
	v_and_b32_e32 v35, 0xffff0000, v33
	v_mul_f32_e32 v33, 0xbfb8aa3b, v34
	v_exp_f32_e32 v33, v33
	s_nop 0
	v_add_f32_e32 v33, 1.0, v33
	v_rcp_f32_e32 v36, v33
	v_mul_f32_e32 v33, 0xbfb8aa3b, v35
	v_exp_f32_e32 v33, v33
	s_nop 0
	v_add_f32_e32 v33, 1.0, v33
	v_rcp_f32_e32 v37, v33
	s_nop 0
	v_pk_mul_f32 v[34:35], v[36:37], v[34:35]
	s_nop 0
	v_pk_mul_f32 v[34:35], v[38:39], v[34:35]
	s_nop 0
	v_cvt_pk_bf16_f32 v33, v34, v35
	global_store_dwordx2 v[48:49], v[32:33], off offset:112
	s_waitcnt vmcnt(15)
	v_mov_b32_e32 v32, v96
	v_mov_b32_e32 v33, v97
	v_lshlrev_b32_e32 v34, 16, v32
	v_and_b32_e32 v35, 0xffff0000, v32
	v_mul_f32_e32 v32, 0xbfb8aa3b, v34
	v_exp_f32_e32 v32, v32
	s_nop 0
	v_add_f32_e32 v32, 1.0, v32
	v_rcp_f32_e32 v36, v32
	v_mul_f32_e32 v32, 0xbfb8aa3b, v35
	v_exp_f32_e32 v32, v32
	s_nop 0
	v_add_f32_e32 v32, 1.0, v32
	v_rcp_f32_e32 v37, v32
	v_lshlrev_b32_e32 v32, 16, v33
	v_and_b32_e32 v33, 0xffff0000, v33
	v_pk_mul_f32 v[34:35], v[36:37], v[34:35]
	s_nop 0
	v_pk_mul_f32 v[16:17], v[16:17], v[34:35]
	s_nop 0
	v_cvt_pk_bf16_f32 v16, v16, v17
	v_mul_f32_e32 v17, 0xbfb8aa3b, v32
	v_exp_f32_e32 v17, v17
	s_nop 0
	v_add_f32_e32 v17, 1.0, v17
	v_rcp_f32_e32 v34, v17
	v_mul_f32_e32 v17, 0xbfb8aa3b, v33
	v_exp_f32_e32 v17, v17
	s_nop 0
	v_add_f32_e32 v17, 1.0, v17
	v_rcp_f32_e32 v35, v17
	s_nop 0
	v_pk_mul_f32 v[32:33], v[34:35], v[32:33]
	s_nop 0
	v_pk_mul_f32 v[18:19], v[18:19], v[32:33]
	s_nop 0
	v_cvt_pk_bf16_f32 v17, v18, v19
	global_store_dwordx2 v[48:49], v[16:17], off offset:128
	s_waitcnt vmcnt(15)
	v_mov_b32_e32 v16, v98
	v_mov_b32_e32 v17, v99
	v_lshlrev_b32_e32 v18, 16, v16
	v_and_b32_e32 v19, 0xffff0000, v16
	v_mul_f32_e32 v16, 0xbfb8aa3b, v18
	v_exp_f32_e32 v16, v16
	s_nop 0
	v_add_f32_e32 v16, 1.0, v16
	v_rcp_f32_e32 v32, v16
	v_mul_f32_e32 v16, 0xbfb8aa3b, v19
	v_exp_f32_e32 v16, v16
	s_nop 0
	v_add_f32_e32 v16, 1.0, v16
	v_rcp_f32_e32 v33, v16
	s_nop 0
	v_pk_mul_f32 v[18:19], v[32:33], v[18:19]
	s_nop 0
	v_pk_mul_f32 v[18:19], v[20:21], v[18:19]
	s_nop 0
	v_cvt_pk_bf16_f32 v16, v18, v19
	v_lshlrev_b32_e32 v18, 16, v17
	v_and_b32_e32 v19, 0xffff0000, v17
	v_mul_f32_e32 v17, 0xbfb8aa3b, v18
	v_exp_f32_e32 v17, v17
	s_nop 0
	v_add_f32_e32 v17, 1.0, v17
	v_rcp_f32_e32 v20, v17
	v_mul_f32_e32 v17, 0xbfb8aa3b, v19
	v_exp_f32_e32 v17, v17
	s_nop 0
	v_add_f32_e32 v17, 1.0, v17
	v_rcp_f32_e32 v21, v17
	s_nop 0
	v_pk_mul_f32 v[18:19], v[20:21], v[18:19]
	s_nop 0
	v_pk_mul_f32 v[18:19], v[22:23], v[18:19]
	v_pk_mul_f32 v[22:23], v[24:25], v[64:65] op_sel_hi:[1,0]
	v_cvt_pk_bf16_f32 v17, v18, v19
	global_store_dwordx2 v[48:49], v[16:17], off offset:144
	s_waitcnt vmcnt(15)
	v_mov_b32_e32 v16, v100
	v_mov_b32_e32 v17, v101
	v_lshlrev_b32_e32 v18, 16, v16
	v_and_b32_e32 v19, 0xffff0000, v16
	v_mul_f32_e32 v16, 0xbfb8aa3b, v18
	v_exp_f32_e32 v16, v16
	s_nop 0
	v_add_f32_e32 v16, 1.0, v16
	v_rcp_f32_e32 v20, v16
	v_mul_f32_e32 v16, 0xbfb8aa3b, v19
	v_exp_f32_e32 v16, v16
	s_nop 0
	v_add_f32_e32 v16, 1.0, v16
	v_rcp_f32_e32 v21, v16
	s_nop 0
	v_pk_mul_f32 v[18:19], v[20:21], v[18:19]
	s_nop 0
	v_pk_mul_f32 v[18:19], v[22:23], v[18:19]
	v_pk_mul_f32 v[22:23], v[26:27], v[64:65] op_sel_hi:[1,0]
	v_cvt_pk_bf16_f32 v16, v18, v19
	v_lshlrev_b32_e32 v18, 16, v17
	v_and_b32_e32 v19, 0xffff0000, v17
	v_mul_f32_e32 v17, 0xbfb8aa3b, v18
	v_exp_f32_e32 v17, v17
	s_nop 0
	v_add_f32_e32 v17, 1.0, v17
	v_rcp_f32_e32 v20, v17
	v_mul_f32_e32 v17, 0xbfb8aa3b, v19
	v_exp_f32_e32 v17, v17
	s_nop 0
	v_add_f32_e32 v17, 1.0, v17
	v_rcp_f32_e32 v21, v17
	s_nop 0
	v_pk_mul_f32 v[18:19], v[20:21], v[18:19]
	s_nop 0
	v_pk_mul_f32 v[18:19], v[22:23], v[18:19]
	v_pk_mul_f32 v[22:23], v[28:29], v[64:65] op_sel_hi:[1,0]
	v_cvt_pk_bf16_f32 v17, v18, v19
	global_store_dwordx2 v[48:49], v[16:17], off offset:160
	s_waitcnt vmcnt(15)
	v_mov_b32_e32 v16, v102
	v_mov_b32_e32 v17, v103
	v_lshlrev_b32_e32 v18, 16, v16
	v_and_b32_e32 v19, 0xffff0000, v16
	v_mul_f32_e32 v16, 0xbfb8aa3b, v18
	v_exp_f32_e32 v16, v16
	s_nop 0
	v_add_f32_e32 v16, 1.0, v16
	v_rcp_f32_e32 v20, v16
	v_mul_f32_e32 v16, 0xbfb8aa3b, v19
	v_exp_f32_e32 v16, v16
	s_nop 0
	v_add_f32_e32 v16, 1.0, v16
	v_rcp_f32_e32 v21, v16
	s_nop 0
	v_pk_mul_f32 v[18:19], v[20:21], v[18:19]
	s_nop 0
	v_pk_mul_f32 v[18:19], v[22:23], v[18:19]
	v_pk_mul_f32 v[22:23], v[30:31], v[64:65] op_sel_hi:[1,0]
	v_cvt_pk_bf16_f32 v16, v18, v19
	v_lshlrev_b32_e32 v18, 16, v17
	v_and_b32_e32 v19, 0xffff0000, v17
	v_mul_f32_e32 v17, 0xbfb8aa3b, v18
	v_exp_f32_e32 v17, v17
	s_nop 0
	v_add_f32_e32 v17, 1.0, v17
	v_rcp_f32_e32 v20, v17
	v_mul_f32_e32 v17, 0xbfb8aa3b, v19
	v_exp_f32_e32 v17, v17
	s_nop 0
	v_add_f32_e32 v17, 1.0, v17
	v_rcp_f32_e32 v21, v17
	s_nop 0
	v_pk_mul_f32 v[18:19], v[20:21], v[18:19]
	s_nop 0
	v_pk_mul_f32 v[18:19], v[22:23], v[18:19]
	s_nop 0
	v_cvt_pk_bf16_f32 v17, v18, v19
	global_store_dwordx2 v[48:49], v[16:17], off offset:176
	s_waitcnt vmcnt(15)
	v_mov_b32_e32 v16, v104
	v_mov_b32_e32 v17, v105
	v_lshlrev_b32_e32 v18, 16, v16
	v_and_b32_e32 v19, 0xffff0000, v16
	v_mul_f32_e32 v16, 0xbfb8aa3b, v18
	v_exp_f32_e32 v16, v16
	s_nop 0
	v_add_f32_e32 v16, 1.0, v16
	v_rcp_f32_e32 v20, v16
	v_mul_f32_e32 v16, 0xbfb8aa3b, v19
	v_exp_f32_e32 v16, v16
	s_nop 0
	v_add_f32_e32 v16, 1.0, v16
	v_rcp_f32_e32 v21, v16
	v_lshlrev_b32_e32 v16, 16, v17
	v_and_b32_e32 v17, 0xffff0000, v17
	v_pk_mul_f32 v[18:19], v[20:21], v[18:19]
	s_nop 0
	v_pk_mul_f32 v[0:1], v[0:1], v[18:19]
	s_nop 0
	v_cvt_pk_bf16_f32 v0, v0, v1
	v_mul_f32_e32 v1, 0xbfb8aa3b, v16
	v_exp_f32_e32 v1, v1
	s_nop 0
	v_add_f32_e32 v1, 1.0, v1
	v_rcp_f32_e32 v18, v1
	v_mul_f32_e32 v1, 0xbfb8aa3b, v17
	v_exp_f32_e32 v1, v1
	s_nop 0
	v_add_f32_e32 v1, 1.0, v1
	v_rcp_f32_e32 v19, v1
	s_nop 0
	v_pk_mul_f32 v[16:17], v[18:19], v[16:17]
	s_nop 0
	v_pk_mul_f32 v[2:3], v[2:3], v[16:17]
	s_nop 0
	v_cvt_pk_bf16_f32 v1, v2, v3
	global_store_dwordx2 v[48:49], v[0:1], off offset:192
	s_waitcnt vmcnt(15)
	v_mov_b32_e32 v0, v106
	v_mov_b32_e32 v1, v107
	v_lshlrev_b32_e32 v2, 16, v0
	v_and_b32_e32 v3, 0xffff0000, v0
	v_mul_f32_e32 v0, 0xbfb8aa3b, v2
	v_exp_f32_e32 v0, v0
	s_nop 0
	v_add_f32_e32 v0, 1.0, v0
	v_rcp_f32_e32 v16, v0
	v_mul_f32_e32 v0, 0xbfb8aa3b, v3
	v_exp_f32_e32 v0, v0
	s_nop 0
	v_add_f32_e32 v0, 1.0, v0
	v_rcp_f32_e32 v17, v0
	s_nop 0
	v_pk_mul_f32 v[2:3], v[16:17], v[2:3]
	s_nop 0
	v_pk_mul_f32 v[2:3], v[4:5], v[2:3]
	s_nop 0
	v_cvt_pk_bf16_f32 v0, v2, v3
	v_lshlrev_b32_e32 v2, 16, v1
	v_and_b32_e32 v3, 0xffff0000, v1
	v_mul_f32_e32 v1, 0xbfb8aa3b, v2
	v_exp_f32_e32 v1, v1
	s_nop 0
	v_add_f32_e32 v1, 1.0, v1
	v_rcp_f32_e32 v4, v1
	v_mul_f32_e32 v1, 0xbfb8aa3b, v3
	v_exp_f32_e32 v1, v1
	s_nop 0
	v_add_f32_e32 v1, 1.0, v1
	v_rcp_f32_e32 v5, v1
	s_nop 0
	v_pk_mul_f32 v[2:3], v[4:5], v[2:3]
	s_nop 0
	v_pk_mul_f32 v[2:3], v[6:7], v[2:3]
	v_pk_mul_f32 v[6:7], v[8:9], v[64:65] op_sel_hi:[1,0]
	v_cvt_pk_bf16_f32 v1, v2, v3
	global_store_dwordx2 v[48:49], v[0:1], off offset:208
	s_waitcnt vmcnt(15)
	v_mov_b32_e32 v0, v108
	v_mov_b32_e32 v1, v109
	v_lshlrev_b32_e32 v2, 16, v0
	v_and_b32_e32 v3, 0xffff0000, v0
	v_mul_f32_e32 v0, 0xbfb8aa3b, v2
	v_exp_f32_e32 v0, v0
	s_nop 0
	v_add_f32_e32 v0, 1.0, v0
	v_rcp_f32_e32 v4, v0
	v_mul_f32_e32 v0, 0xbfb8aa3b, v3
	v_exp_f32_e32 v0, v0
	s_nop 0
	v_add_f32_e32 v0, 1.0, v0
	v_rcp_f32_e32 v5, v0
	s_nop 0
	v_pk_mul_f32 v[2:3], v[4:5], v[2:3]
	s_nop 0
	v_pk_mul_f32 v[2:3], v[6:7], v[2:3]
	v_pk_mul_f32 v[6:7], v[10:11], v[64:65] op_sel_hi:[1,0]
	v_cvt_pk_bf16_f32 v0, v2, v3
	v_lshlrev_b32_e32 v2, 16, v1
	v_and_b32_e32 v3, 0xffff0000, v1
	v_mul_f32_e32 v1, 0xbfb8aa3b, v2
	v_exp_f32_e32 v1, v1
	s_nop 0
	v_add_f32_e32 v1, 1.0, v1
	v_rcp_f32_e32 v4, v1
	v_mul_f32_e32 v1, 0xbfb8aa3b, v3
	v_exp_f32_e32 v1, v1
	s_nop 0
	v_add_f32_e32 v1, 1.0, v1
	v_rcp_f32_e32 v5, v1
	s_nop 0
	v_pk_mul_f32 v[2:3], v[4:5], v[2:3]
	s_nop 0
	v_pk_mul_f32 v[2:3], v[6:7], v[2:3]
	v_pk_mul_f32 v[6:7], v[12:13], v[64:65] op_sel_hi:[1,0]
	v_cvt_pk_bf16_f32 v1, v2, v3
	global_store_dwordx2 v[48:49], v[0:1], off offset:224
	s_waitcnt vmcnt(15)
	v_mov_b32_e32 v0, v110
	v_mov_b32_e32 v1, v111
	v_lshlrev_b32_e32 v2, 16, v0
	v_and_b32_e32 v3, 0xffff0000, v0
	v_mul_f32_e32 v0, 0xbfb8aa3b, v2
	v_exp_f32_e32 v0, v0
	s_nop 0
	v_add_f32_e32 v0, 1.0, v0
	v_rcp_f32_e32 v4, v0
	v_mul_f32_e32 v0, 0xbfb8aa3b, v3
	v_exp_f32_e32 v0, v0
	s_nop 0
	v_add_f32_e32 v0, 1.0, v0
	v_rcp_f32_e32 v5, v0
	s_nop 0
	v_pk_mul_f32 v[2:3], v[4:5], v[2:3]
	s_nop 0
	v_pk_mul_f32 v[2:3], v[6:7], v[2:3]
	v_pk_mul_f32 v[6:7], v[14:15], v[64:65] op_sel_hi:[1,0]
	v_cvt_pk_bf16_f32 v0, v2, v3
	v_lshlrev_b32_e32 v2, 16, v1
	v_and_b32_e32 v3, 0xffff0000, v1
	v_mul_f32_e32 v1, 0xbfb8aa3b, v2
	v_exp_f32_e32 v1, v1
	s_nop 0
	v_add_f32_e32 v1, 1.0, v1
	v_rcp_f32_e32 v4, v1
	v_mul_f32_e32 v1, 0xbfb8aa3b, v3
	v_exp_f32_e32 v1, v1
	s_nop 0
	v_add_f32_e32 v1, 1.0, v1
	v_rcp_f32_e32 v5, v1
	s_nop 0
	v_pk_mul_f32 v[2:3], v[4:5], v[2:3]
	s_nop 0
	v_pk_mul_f32 v[2:3], v[6:7], v[2:3]
	s_nop 0
	v_cvt_pk_bf16_f32 v1, v2, v3
	global_store_dwordx2 v[48:49], v[0:1], off offset:240
	s_barrier
